# unit map in 12 GEMM unit loops: group size is always 8, so the float-rcp/Newton integer division became a shift and a mask
# baseline (speedup 1.0000x reference)
;     __device__ __forceinline__ bool next(int i, Unit& u) const { const long L = (long)i * G + c; if (L >= map.total()) return false; map((int)L, u); return true; }
.LBB0_253:
	s_add_i32 s43, s43, 1
	s_mul_i32 s4, s43, s3
	s_mul_hi_u32 s5, s43, s90
	s_add_i32 s5, s5, s4
	s_mul_i32 s4, s43, s90
	s_add_u32 s28, s4, s2
	s_addc_u32 s29, s5, s70
	v_cmp_gt_i64_e32 vcc, s[28:29], v[138:139]
	v_cmp_lt_i64_e64 s[4:5], s[28:29], v[136:137]
	s_cbranch_vccnz .LBB0_255
	s_ashr_i32 s12, s28, 31
	s_lshr_b32 s12, s12, 29
	s_add_i32 s12, s28, s12
	s_ashr_i32 s13, s12, 3
	s_and_b32 s12, s12, -8
	s_sub_i32 s12, s28, s12
	s_cmp_lt_i32 s12, 0
	s_cselect_b32 s22, s21, 0x176
	s_mul_i32 s12, s12, s22
	s_add_i32 s12, s12, s13
	s_mul_hi_i32 s13, s12, 0x2e8ba2e9
	s_lshr_b32 s22, s13, 31
	s_ashr_i32 s13, s13, 5
	s_add_i32 s13, s13, s22
	s_lshl_b32 s22, s13, 3
	s_mulk_i32 s13, 0xb0
	s_sub_i32 s13, s12, s13
	s_lshr_b32 s12, s13, 3
	s_and_b32 s13, s13, 7
	s_add_i32 s22, s22, s13
	s_ashr_i32 s23, s22, 31
	s_ashr_i32 s13, s12, 31
	s_lshl_b64 s[24:25], s[22:23], 19
	s_lshl_b64 s[26:27], s[12:13], 19

.LBB0_483:
	s_add_i32 s47, s47, 1
	s_mul_i32 s4, s47, s3
	s_mul_hi_u32 s5, s47, s90
	s_add_i32 s5, s5, s4
	s_mul_i32 s4, s47, s90
	s_add_u32 s36, s4, s2
	s_addc_u32 s37, s5, s70
	v_cmp_gt_i64_e32 vcc, s[36:37], v[144:145]
	v_cmp_lt_i64_e64 s[4:5], s[36:37], v[142:143]
	s_cbranch_vccnz .LBB0_485
	s_ashr_i32 s7, s36, 31
	s_lshr_b32 s7, s7, 29
	s_add_i32 s7, s36, s7
	s_ashr_i32 s12, s7, 3
	s_and_b32 s7, s7, -8
	s_sub_i32 s7, s36, s7
	s_cmp_lt_i32 s7, 0
	s_cselect_b32 s13, s34, 0x55
	s_mul_i32 s7, s7, s13
	s_add_i32 s7, s7, s12
	s_mul_hi_i32 s12, s7, 0x66666667
	s_lshr_b32 s13, s12, 31
	s_ashr_i32 s12, s12, 4
	s_add_i32 s12, s12, s13
	s_lshl_b32 s13, s12, 3
	s_mul_i32 s12, s12, 40
	s_sub_i32 s7, s7, s12
	s_lshr_b32 s12, s7, 3
	s_and_b32 s7, s7, 7
	s_add_i32 s24, s13, s7
	s_ashr_i32 s25, s24, 31
	s_ashr_i32 s13, s12, 31
	s_lshl_b64 s[26:27], s[24:25], 19
	s_lshl_b64 s[28:29], s[12:13], 19

.LBB0_840:
	s_ashr_i32 s22, s24, 3
	s_add_i32 s22, s26, s22
	s_ashr_i32 s23, s22, 31
	s_lshr_b32 s23, s23, 28
	s_add_i32 s23, s22, s23
	s_ashr_i32 s24, s23, 4
	s_lshl_b32 s24, s24, 3
	s_and_b32 s23, s23, -16
	s_sub_i32 s27, s22, s23
	s_lshr_b32 s22, s27, 3
	s_and_b32 s25, s27, 7
	s_add_i32 s24, s24, s25
	s_ashr_i32 s23, s22, 31
	s_ashr_i32 s25, s24, 31
	s_lshl_b64 s[26:27], s[24:25], 13
	s_lshl_b64 s[28:29], s[22:23], 18

.LBB0_916:
	s_ashr_i32 s22, s24, 3
	s_add_i32 s22, s26, s22
	s_ashr_i32 s23, s22, 31
	s_lshr_b32 s23, s23, 27
	s_add_i32 s23, s22, s23
	s_ashr_i32 s24, s23, 5
	s_lshl_b32 s24, s24, 3
	s_andn2_b32 s23, s23, 31
	s_sub_i32 s27, s22, s23
	s_lshr_b32 s22, s27, 3
	s_and_b32 s25, s27, 7
	s_add_i32 s24, s24, s25
	s_ashr_i32 s23, s22, 31
	s_ashr_i32 s25, s24, 31
	s_lshl_b64 s[26:27], s[24:25], 19
	s_lshl_b64 s[28:29], s[22:23], 19

;     __device__ __forceinline__ bool next(int i, Unit& u) const { const long L = (long)i * G + c; if (L >= map.total()) return false; map((int)L, u); return true; }
.LBB0_1041:
	s_add_i32 s52, s52, 1
	s_mul_i32 s4, s52, s3
	s_mul_hi_u32 s5, s52, s90
	s_add_i32 s5, s5, s4
	s_mul_i32 s4, s52, s90
	s_add_u32 s36, s4, s2
	s_addc_u32 s37, s5, s70
	v_cmp_gt_i64_e32 vcc, s[36:37], v[138:139]
	v_cmp_lt_i64_e64 s[4:5], s[36:37], v[136:137]
	s_cbranch_vccnz .LBB0_1043
	s_ashr_i32 s24, s36, 31
	s_lshr_b32 s24, s24, 29
	s_add_i32 s24, s36, s24
	s_ashr_i32 s25, s24, 3
	s_and_b32 s24, s24, -8
	s_sub_i32 s24, s36, s24
	s_cmp_lt_i32 s24, 0
	s_cselect_b32 s26, s31, 0x160
	s_mul_i32 s24, s24, s26
	s_add_i32 s24, s24, s25
	s_mul_hi_i32 s25, s24, 0x2e8ba2e9
	s_lshr_b32 s26, s25, 31
	s_ashr_i32 s25, s25, 5
	s_add_i32 s25, s25, s26
	s_lshl_b32 s26, s25, 3
	s_mulk_i32 s25, 0xb0
	s_sub_i32 s25, s24, s25
	s_lshr_b32 s24, s25, 3
	s_and_b32 s25, s25, 7
	s_add_i32 s26, s26, s25
	s_ashr_i32 s27, s26, 31
	s_ashr_i32 s25, s24, 31
	s_lshl_b64 s[28:29], s[26:27], 19
	s_lshl_b64 s[34:35], s[24:25], 19

.LBB0_1119:
	s_ashr_i32 s22, s24, 3
	s_add_i32 s22, s26, s22
	s_ashr_i32 s23, s22, 31
	s_lshr_b32 s23, s23, 27
	s_add_i32 s23, s22, s23
	s_ashr_i32 s24, s23, 5
	s_lshl_b32 s24, s24, 3
	s_andn2_b32 s23, s23, 31
	s_sub_i32 s22, s22, s23
	s_lshr_b32 s54, s22, 3
	s_and_b32 s22, s22, 7
	s_add_i32 s55, s24, s22
	s_mul_hi_i32 s23, s55, 0x160000
	s_mul_i32 s22, s55, 0x160000
	s_mul_hi_i32 s25, s54, 0x160000
	s_mul_i32 s24, s54, 0x160000

;     __device__ __forceinline__ bool next(int i, Unit& u) const { const long L = (long)i * G + c; if (L >= map.total()) return false; map((int)L, u); return true; }
.LBB0_1244:
	s_add_i32 s52, s52, 1
	s_mul_i32 s6, s52, s3
	s_mul_hi_u32 s7, s52, s90
	s_add_i32 s7, s7, s6
	s_mul_i32 s6, s52, s90
	s_add_u32 s36, s6, s2
	s_addc_u32 s37, s7, s70
	v_cmp_gt_i64_e32 vcc, s[36:37], v[138:139]
	v_cmp_lt_i64_e64 s[6:7], s[36:37], v[136:137]
	s_cbranch_vccnz .LBB0_1246
	s_ashr_i32 s24, s36, 31
	s_lshr_b32 s24, s24, 29
	s_add_i32 s24, s36, s24
	s_ashr_i32 s25, s24, 3
	s_and_b32 s24, s24, -8
	s_sub_i32 s24, s36, s24
	s_cmp_lt_i32 s24, 0
	s_cselect_b32 s26, s31, 0x160
	s_mul_i32 s24, s24, s26
	s_add_i32 s24, s24, s25
	s_mul_hi_i32 s25, s24, 0x2e8ba2e9
	s_lshr_b32 s26, s25, 31
	s_ashr_i32 s25, s25, 5
	s_add_i32 s25, s25, s26
	s_lshl_b32 s26, s25, 3
	s_mulk_i32 s25, 0xb0
	s_sub_i32 s25, s24, s25
	s_lshr_b32 s24, s25, 3
	s_and_b32 s25, s25, 7
	s_add_i32 s26, s26, s25
	s_ashr_i32 s27, s26, 31
	s_ashr_i32 s25, s24, 31
	s_lshl_b64 s[28:29], s[26:27], 19
	s_lshl_b64 s[34:35], s[24:25], 19

;     __device__ __forceinline__ bool next(int i, Unit& u) const { const long L = (long)i * G + c; if (L >= map.total()) return false; map((int)L, u); return true; }
.LBB0_1528:
	s_add_i32 s51, s51, 1
	s_mul_i32 s6, s51, s3
	s_mul_hi_u32 s7, s51, s90
	s_add_i32 s7, s7, s6
	s_mul_i32 s6, s51, s90
	s_add_u32 s36, s6, s2
	s_addc_u32 s37, s7, s70
	v_cmp_gt_i64_e32 vcc, s[36:37], v[140:141]
	v_cmp_lt_i64_e64 s[6:7], s[36:37], v[138:139]
	s_cbranch_vccnz .LBB0_1530
	s_ashr_i32 s9, s36, 31
	s_lshr_b32 s9, s9, 29
	s_add_i32 s9, s36, s9
	s_ashr_i32 s24, s9, 3
	s_and_b32 s9, s9, -8
	s_sub_i32 s9, s36, s9
	s_cmp_lt_i32 s9, 0
	s_cselect_b32 s25, s54, 0x48
	s_mul_i32 s9, s9, s25
	s_add_i32 s9, s9, s24
	s_ashr_i32 s24, s9, 31
	s_lshr_b32 s24, s24, 28
	s_add_i32 s24, s9, s24
	s_ashr_i32 s25, s24, 4
	s_lshl_b32 s25, s25, 3
	s_and_b32 s24, s24, -16
	s_sub_i32 s9, s9, s24
	s_lshr_b32 s24, s9, 3
	s_and_b32 s9, s9, 7
	s_add_i32 s26, s25, s9
	s_ashr_i32 s27, s26, 31
	s_ashr_i32 s25, s24, 31
	s_lshl_b64 s[28:29], s[26:27], 18
	s_lshl_b64 s[34:35], s[24:25], 18

;     __device__ __forceinline__ bool next(int i, Unit& u) const { const long L = (long)i * G + c; if (L >= map.total()) return false; map((int)L, u); return true; }
.LBB0_1860:
	s_add_i32 s47, s47, 1
	s_mul_i32 s6, s47, s3
	s_mul_hi_u32 s7, s47, s90
	s_add_i32 s7, s7, s6
	s_mul_i32 s6, s47, s90
	s_add_u32 s28, s6, s2
	s_addc_u32 s29, s7, s70
	v_cmp_gt_i64_e32 vcc, s[28:29], v[138:139]
	v_cmp_lt_i64_e64 s[6:7], s[28:29], v[136:137]
	s_cbranch_vccnz .LBB0_1862
	s_ashr_i32 s20, s28, 31
	s_lshr_b32 s20, s20, 29
	s_add_i32 s20, s28, s20
	s_ashr_i32 s21, s20, 3
	s_and_b32 s20, s20, -8
	s_sub_i32 s20, s28, s20
	s_cmp_lt_i32 s20, 0
	s_cselect_b32 s22, s43, 0x160
	s_mul_i32 s20, s20, s22
	s_add_i32 s20, s20, s21
	s_mul_hi_i32 s21, s20, 0x2e8ba2e9
	s_lshr_b32 s22, s21, 31
	s_ashr_i32 s21, s21, 5
	s_add_i32 s21, s21, s22
	s_lshl_b32 s22, s21, 3
	s_mulk_i32 s21, 0xb0
	s_sub_i32 s21, s20, s21
	s_lshr_b32 s20, s21, 3
	s_and_b32 s21, s21, 7
	s_add_i32 s22, s22, s21
	s_ashr_i32 s23, s22, 31
	s_ashr_i32 s21, s20, 31
	s_lshl_b64 s[24:25], s[22:23], 19
	s_lshl_b64 s[26:27], s[20:21], 19

.LBB0_1938:
	s_ashr_i32 s10, s12, 3
	s_add_i32 s10, s16, s10
	s_ashr_i32 s11, s10, 31
	s_lshr_b32 s11, s11, 27
	s_add_i32 s11, s10, s11
	s_ashr_i32 s12, s11, 5
	s_lshl_b32 s12, s12, 3
	s_andn2_b32 s11, s11, 31
	s_sub_i32 s10, s10, s11
	s_lshr_b32 s43, s10, 3
	s_and_b32 s10, s10, 7
	s_add_i32 s44, s12, s10
	s_mul_hi_i32 s11, s44, 0x160000
	s_mul_i32 s10, s44, 0x160000
	s_mul_hi_i32 s13, s43, 0x160000
	s_mul_i32 s12, s43, 0x160000
